# no accumulator zeroing: phases 1-2 of each unit's first K iteration peeled, first MFMA per accumulator takes C=0 (on top of split barrier, no-op step skip, write-through stores)
# speedup vs baseline: 1.0233x; 1.0103x over previous
; #define PG8_STAGE(bufoff, gbase, voff) do { _Pragma("unroll") for (int _i = 0; _i < 2; ++_i) { unsigned _vo = (voff)[_i]; asm volatile("" : "+v"(_vo));   \
;         __builtin_amdgcn_global_load_lds((const unsigned*)((const char*)(gbase) + _vo), (LAS unsigned*)(lds + (bufoff) + ldsw + _i * 8192), 16, 0, 0); } } while (0)
; #define PG8_LDA(dst, b, h) do { _Pragma("unroll") for (int m = 0; m < 4; ++m) _Pragma("unroll") for (int k = 0; k < 2; ++k) dst[m][k] = *(const LAS bf16x8*)(lds + PG8_SA(b, h) + aoff + m * 2048 + k * 1024); } while (0)
; #define PG8_LDB(dst, b, h) do { _Pragma("unroll") for (int n = 0; n < 2; ++n) _Pragma("unroll") for (int k = 0; k < 2; ++k) dst[n][k] = *(const LAS bf16x8*)(lds + PG8_SB(b, h) + boff + n * 2048 + k * 1024); } while (0)
; #define PG8_WAIT_V(n) asm volatile("s_waitcnt vmcnt(" #n ")" ::: "memory")
; #define PG8_WAIT_L(n) asm volatile("s_waitcnt lgkmcnt(" #n ")" ::: "memory")
; #define PG8_BAR __builtin_amdgcn_s_barrier()
; #define PG8_SCHED __builtin_amdgcn_sched_barrier(0)
; __device__ __forceinline__ void gemm_phase(LAS unsigned char* lds, const Call& C, const int tid, const Args& args) {
;     ...
;     f32x4 acc[2][2][4][2];
; #pragma unroll
;     for (int a = 0; a < 2; ++a)
; #pragma unroll
;         for (int b = 0; b < 2; ++b)
; #pragma unroll
;             for (int m = 0; m < 4; ++m)
; #pragma unroll
;                 for (int n = 0; n < 2; ++n) acc[a][b][m][n] = (f32x4){0.f, 0.f, 0.f, 0.f};
;     ...
;         for (int t = 0; t < nt; t += 2) {
;             const bool last = (t == nt - 2);
;             const char* a1 = cA + (size_t)(t + 1) * kstep;
;             const char* a2 = last ? nA : cA + (size_t)(t + 2) * kstep; const char* b2 = last ? nB : cB + (size_t)(t + 2) * kstep;
;             const char* a3 = a2 + kstep; const char* b3 = b2 + kstep;
;             PG8_LDB(B0, 0, 0); PG8_LDB(B1, 0, 1); PG8_SCHED; PG8_LDA(At, 0, 0); PG8_STAGE(PG8_SA(1, 1), a1 + hstepA, voffA);
;             PG8_WAIT_V(8); PG8_WAIT_L(0); PG8_BAR; PG8_MMA(0, 0, At, B0); PG8_MMA(0, 1, At, B1); PG8_BAR; PG8_SCHED;
;             PG8_LDA(At, 0, 1); PG8_STAGE(PG8_SB(0, 0), b2, voffB); PG8_STAGE(PG8_SB(0, 1), b2 + hstepB, voffB); PG8_STAGE(PG8_SA(0, 0), a2, voffA);
;             PG8_WAIT_V(8); PG8_WAIT_L(0); PG8_BAR; PG8_MMA(1, 0, At, B0); PG8_MMA(1, 1, At, B1); PG8_BAR; PG8_SCHED;
.LBB0_280:
	s_cmp_eq_u32 s16, 0
	s_cbranch_scc1 .LBB0_313
	s_lshl_b32 s12, s16, 1
	s_add_i32 s13, s12, -2
	s_add_u32 s16, s8, 0x100
	s_addc_u32 s17, s9, 0
	s_mov_b32 s24, 0
	s_waitcnt lgkmcnt(0)
	s_add_i32 s25, s24, 2
	s_add_u32 s8, s0, 0x100
	s_addc_u32 s9, s1, 0
	s_add_i32 s34, 0, 0x10000
	s_cmp_eq_u32 s13, s24
	s_cselect_b32 s39, s87, s9
	s_cselect_b32 s38, s86, s8
	v_add_u32_e32 v80, s34, v245
	s_cselect_b32 s41, s49, s17
	s_cselect_b32 s40, s48, s16
	s_add_i32 s24, 0, 0x14000
	ds_read_b128 v[136:139], v80
	ds_read_b128 v[140:143], v80 offset:1024
	ds_read_b128 v[144:147], v80 offset:2048
	ds_read_b128 v[148:151], v80 offset:3072
	v_add_u32_e32 v80, s24, v245
	ds_read_b128 v[152:155], v80
	ds_read_b128 v[156:159], v80 offset:1024
	ds_read_b128 v[160:163], v80 offset:2048
	ds_read_b128 v[164:167], v80 offset:3072
	v_mov_b32_e32 v80, v205
	s_add_u32 s0, s0, s89
	ds_read_b128 v[168:171], v246
	ds_read_b128 v[172:175], v246 offset:1024
	ds_read_b128 v[176:179], v246 offset:2048
	ds_read_b128 v[180:183], v246 offset:3072
	ds_read_b128 v[184:187], v246 offset:4096
	ds_read_b128 v[188:191], v246 offset:5120
	ds_read_b128 v[192:195], v246 offset:6144
	ds_read_b128 v[196:199], v246 offset:7168
	s_addc_u32 s1, s1, s94
	s_add_i32 m0, s20, 0xc000
	s_nop 0
	global_load_lds_dwordx4 v80, s[0:1]
	v_mov_b32_e32 v80, v243
	s_add_i32 m0, s20, 0xe000
	s_nop 0
	global_load_lds_dwordx4 v80, s[0:1]
	s_waitcnt vmcnt(8)
	s_waitcnt lgkmcnt(0)
	s_barrier
	s_setprio 1
	s_waitcnt lgkmcnt(0)
	v_mfma_f32_16x16x32_bf16 v[132:135], v[136:139], v[168:171], 0
	v_mfma_f32_16x16x32_bf16 v[128:131], v[144:147], v[168:171], 0
	v_mfma_f32_16x16x32_bf16 v[124:127], v[136:139], v[176:179], 0
	v_mfma_f32_16x16x32_bf16 v[120:123], v[144:147], v[176:179], 0
	v_mfma_f32_16x16x32_bf16 v[108:111], v[136:139], v[184:187], 0
	v_mfma_f32_16x16x32_bf16 v[104:107], v[144:147], v[184:187], 0
	v_mfma_f32_16x16x32_bf16 v[92:95], v[136:139], v[192:195], 0
	v_mfma_f32_16x16x32_bf16 v[86:89], v[144:147], v[192:195], 0
	v_mfma_f32_16x16x32_bf16 v[132:135], v[140:143], v[172:175], v[132:135]
	v_mfma_f32_16x16x32_bf16 v[128:131], v[148:151], v[172:175], v[128:131]
	v_mfma_f32_16x16x32_bf16 v[124:127], v[140:143], v[180:183], v[124:127]
	v_mfma_f32_16x16x32_bf16 v[120:123], v[148:151], v[180:183], v[120:123]
	v_mfma_f32_16x16x32_bf16 v[108:111], v[140:143], v[188:191], v[108:111]
	v_mfma_f32_16x16x32_bf16 v[104:107], v[148:151], v[188:191], v[104:107]
	v_mfma_f32_16x16x32_bf16 v[92:95], v[140:143], v[196:199], v[92:95]
	v_mfma_f32_16x16x32_bf16 v[86:89], v[148:151], v[196:199], v[86:89]
	s_setprio 0
	s_setprio 1
	v_mfma_f32_16x16x32_bf16 v[116:119], v[152:155], v[168:171], 0
	v_mfma_f32_16x16x32_bf16 v[112:115], v[160:163], v[168:171], 0
	v_mfma_f32_16x16x32_bf16 v[100:103], v[152:155], v[176:179], 0
	v_mfma_f32_16x16x32_bf16 v[96:99], v[160:163], v[176:179], 0
	v_mfma_f32_16x16x32_bf16 v[76:79], v[152:155], v[184:187], 0
	v_mfma_f32_16x16x32_bf16 v[72:75], v[160:163], v[184:187], 0
	v_mfma_f32_16x16x32_bf16 v[68:71], v[152:155], v[192:195], 0
	v_mfma_f32_16x16x32_bf16 v[60:63], v[160:163], v[192:195], 0
	v_mfma_f32_16x16x32_bf16 v[116:119], v[156:159], v[172:175], v[116:119]
	v_mfma_f32_16x16x32_bf16 v[112:115], v[164:167], v[172:175], v[112:115]
	v_mfma_f32_16x16x32_bf16 v[100:103], v[156:159], v[180:183], v[100:103]
	v_mfma_f32_16x16x32_bf16 v[96:99], v[164:167], v[180:183], v[96:99]
	v_mfma_f32_16x16x32_bf16 v[76:79], v[156:159], v[188:191], v[76:79]
	v_mfma_f32_16x16x32_bf16 v[72:75], v[164:167], v[188:191], v[72:75]
	v_mfma_f32_16x16x32_bf16 v[68:71], v[156:159], v[196:199], v[68:71]
	v_mfma_f32_16x16x32_bf16 v[60:63], v[164:167], v[196:199], v[60:63]
	s_setprio 0
	s_barrier
	v_mov_b32_e32 v80, v242
	s_add_i32 s0, s34, s23
	ds_read_b128 v[168:171], v246 offset:16384
	ds_read_b128 v[172:175], v246 offset:17408
	ds_read_b128 v[176:179], v246 offset:18432
	ds_read_b128 v[180:183], v246 offset:19456
	ds_read_b128 v[184:187], v246 offset:20480
	ds_read_b128 v[188:191], v246 offset:21504
	ds_read_b128 v[192:195], v246 offset:22528
	ds_read_b128 v[196:199], v246 offset:23552
	s_mov_b32 m0, s0
	s_nop 0
	global_load_lds_dwordx4 v80, s[40:41]
	v_mov_b32_e32 v80, v244
	s_add_i32 m0, s0, 0x2000
	s_add_u32 s0, s40, s74
	global_load_lds_dwordx4 v80, s[40:41]
	s_addc_u32 s1, s41, s75
	v_mov_b32_e32 v80, v242
	s_add_i32 s24, s24, s23
	s_mov_b32 m0, s24
	s_nop 0
	global_load_lds_dwordx4 v80, s[0:1]
	v_mov_b32_e32 v80, v244
	s_add_i32 m0, s24, 0x2000
	s_nop 0
	global_load_lds_dwordx4 v80, s[0:1]
	v_mov_b32_e32 v80, v205
	s_mov_b32 m0, s20
	s_nop 0
	global_load_lds_dwordx4 v80, s[38:39]
	v_mov_b32_e32 v80, v243
	s_mov_b32 m0, s72
	s_nop 0
	global_load_lds_dwordx4 v80, s[38:39]
	s_waitcnt vmcnt(8)
	s_waitcnt lgkmcnt(0)
	s_barrier
	s_setprio 1
	s_waitcnt lgkmcnt(0)
	v_mfma_f32_16x16x32_bf16 v[64:67], v[136:139], v[168:171], 0
	v_mfma_f32_16x16x32_bf16 v[56:59], v[144:147], v[168:171], 0
	v_mfma_f32_16x16x32_bf16 v[52:55], v[136:139], v[176:179], 0
	v_mfma_f32_16x16x32_bf16 v[48:51], v[144:147], v[176:179], 0
	v_mfma_f32_16x16x32_bf16 v[36:39], v[136:139], v[184:187], 0
	v_mfma_f32_16x16x32_bf16 v[32:35], v[144:147], v[184:187], 0
	v_mfma_f32_16x16x32_bf16 v[20:23], v[136:139], v[192:195], 0
	v_mfma_f32_16x16x32_bf16 v[16:19], v[144:147], v[192:195], 0
	v_mfma_f32_16x16x32_bf16 v[64:67], v[140:143], v[172:175], v[64:67]
	v_mfma_f32_16x16x32_bf16 v[56:59], v[148:151], v[172:175], v[56:59]
	v_mfma_f32_16x16x32_bf16 v[52:55], v[140:143], v[180:183], v[52:55]
	v_mfma_f32_16x16x32_bf16 v[48:51], v[148:151], v[180:183], v[48:51]
	v_mfma_f32_16x16x32_bf16 v[36:39], v[140:143], v[188:191], v[36:39]
	v_mfma_f32_16x16x32_bf16 v[32:35], v[148:151], v[188:191], v[32:35]
	v_mfma_f32_16x16x32_bf16 v[20:23], v[140:143], v[196:199], v[20:23]
	v_mfma_f32_16x16x32_bf16 v[16:19], v[148:151], v[196:199], v[16:19]
	s_setprio 0
	s_setprio 1
	v_mfma_f32_16x16x32_bf16 v[44:47], v[152:155], v[168:171], 0
	v_mfma_f32_16x16x32_bf16 v[40:43], v[160:163], v[168:171], 0
	v_mfma_f32_16x16x32_bf16 v[28:31], v[152:155], v[176:179], 0
	v_mfma_f32_16x16x32_bf16 v[24:27], v[160:163], v[176:179], 0
	v_mfma_f32_16x16x32_bf16 v[12:15], v[152:155], v[184:187], 0
	v_mfma_f32_16x16x32_bf16 v[8:11], v[160:163], v[184:187], 0
	v_mfma_f32_16x16x32_bf16 v[4:7], v[152:155], v[192:195], 0
	v_mfma_f32_16x16x32_bf16 v[0:3], v[160:163], v[192:195], 0
	v_mfma_f32_16x16x32_bf16 v[44:47], v[156:159], v[172:175], v[44:47]
	v_mfma_f32_16x16x32_bf16 v[40:43], v[164:167], v[172:175], v[40:43]
	v_mfma_f32_16x16x32_bf16 v[28:31], v[156:159], v[180:183], v[28:31]
	v_mfma_f32_16x16x32_bf16 v[24:27], v[164:167], v[180:183], v[24:27]
	v_mfma_f32_16x16x32_bf16 v[12:15], v[156:159], v[188:191], v[12:15]
	v_mfma_f32_16x16x32_bf16 v[8:11], v[164:167], v[188:191], v[8:11]
	v_mfma_f32_16x16x32_bf16 v[4:7], v[156:159], v[196:199], v[4:7]
	v_mfma_f32_16x16x32_bf16 v[0:3], v[164:167], v[196:199], v[0:3]
	s_setprio 0
	s_barrier
	s_branch .Lp7_ph3

; #define PG8_STAGE(bufoff, gbase, voff) do { _Pragma("unroll") for (int _i = 0; _i < 2; ++_i) { unsigned _vo = (voff)[_i]; asm volatile("" : "+v"(_vo));   \
;         __builtin_amdgcn_global_load_lds((const unsigned*)((const char*)(gbase) + _vo), (LAS unsigned*)(lds + (bufoff) + ldsw + _i * 8192), 16, 0, 0); } } while (0)
; #define PG8_LDA(dst, b, h) do { _Pragma("unroll") for (int m = 0; m < 4; ++m) _Pragma("unroll") for (int k = 0; k < 2; ++k) dst[m][k] = *(const LAS bf16x8*)(lds + PG8_SA(b, h) + aoff + m * 2048 + k * 1024); } while (0)
; #define PG8_LDB(dst, b, h) do { _Pragma("unroll") for (int n = 0; n < 2; ++n) _Pragma("unroll") for (int k = 0; k < 2; ++k) dst[n][k] = *(const LAS bf16x8*)(lds + PG8_SB(b, h) + boff + n * 2048 + k * 1024); } while (0)
; #define PG8_MMA(ai, bj, At, Bt) do { __builtin_amdgcn_s_setprio(1); _Pragma("unroll") for (int m = 0; m < 4; ++m) _Pragma("unroll") for (int n = 0; n < 2; ++n) _Pragma("unroll") for (int k = 0; k < 2; ++k) \
;         acc[ai][bj][m][n] = __builtin_amdgcn_mfma_f32_16x16x32_bf16(Bt[n][k], At[m][k], acc[ai][bj][m][n], 0, 0, 0); __builtin_amdgcn_s_setprio(0); } while (0)
; #define PG8_WAIT_V(n) asm volatile("s_waitcnt vmcnt(" #n ")" ::: "memory")
; #define PG8_WAIT_L(n) asm volatile("s_waitcnt lgkmcnt(" #n ")" ::: "memory")
; #define PG8_BAR __builtin_amdgcn_s_barrier()
; #define PG8_SCHED __builtin_amdgcn_sched_barrier(0)
; __device__ __forceinline__ void gemm_phase(LAS unsigned char* lds, const Call& C, const int tid, const Args& args) {
;     ...
;             PG8_LDB(B0, 1, 0); PG8_LDB(B1, 1, 1); PG8_SCHED; PG8_LDA(At, 1, 0); PG8_STAGE(PG8_SA(0, 1), a2 + hstepA, voffA);
;             PG8_WAIT_V(8); PG8_WAIT_L(0); PG8_BAR; PG8_MMA(0, 0, At, B0); PG8_MMA(0, 1, At, B1); PG8_BAR; PG8_SCHED;
.Lp7_ph3:
	s_add_i32 s24, 0, 0x18000
	v_add_u32_e32 v80, s24, v245
	s_add_i32 s42, 0, 0x1c000
	ds_read_b128 v[136:139], v80
	ds_read_b128 v[140:143], v80 offset:1024
	ds_read_b128 v[144:147], v80 offset:2048
	ds_read_b128 v[148:151], v80 offset:3072
	v_add_u32_e32 v80, s42, v245
	ds_read_b128 v[152:155], v80
	ds_read_b128 v[156:159], v80 offset:1024
	ds_read_b128 v[160:163], v80 offset:2048
	ds_read_b128 v[164:167], v80 offset:3072
	s_add_u32 s34, s38, s22
	v_mov_b32_e32 v80, v205
	s_mov_b32 m0, s73
	ds_read_b128 v[168:171], v246 offset:32768
	ds_read_b128 v[172:175], v246 offset:33792
	ds_read_b128 v[176:179], v246 offset:34816
	ds_read_b128 v[180:183], v246 offset:35840
	ds_read_b128 v[184:187], v246 offset:36864
	ds_read_b128 v[188:191], v246 offset:37888
	ds_read_b128 v[192:195], v246 offset:38912
	ds_read_b128 v[196:199], v246 offset:39936
	s_addc_u32 s35, s39, 0
	s_nop 0
	global_load_lds_dwordx4 v80, s[34:35]
	v_mov_b32_e32 v80, v243
	s_mov_b32 m0, s4
	s_nop 0
	global_load_lds_dwordx4 v80, s[34:35]
	s_waitcnt vmcnt(8)
	s_waitcnt lgkmcnt(0)
	s_barrier
	s_setprio 1
	s_waitcnt lgkmcnt(0)
	v_mfma_f32_16x16x32_bf16 v[132:135], v[136:139], v[168:171], v[132:135]
	v_mfma_f32_16x16x32_bf16 v[128:131], v[144:147], v[168:171], v[128:131]
	v_mfma_f32_16x16x32_bf16 v[124:127], v[136:139], v[176:179], v[124:127]
	v_mfma_f32_16x16x32_bf16 v[120:123], v[144:147], v[176:179], v[120:123]
	v_mfma_f32_16x16x32_bf16 v[108:111], v[136:139], v[184:187], v[108:111]
	v_mfma_f32_16x16x32_bf16 v[104:107], v[144:147], v[184:187], v[104:107]
	v_mfma_f32_16x16x32_bf16 v[90:93], v[136:139], v[192:195], v[92:95]
	v_mfma_f32_16x16x32_bf16 v[86:89], v[144:147], v[192:195], v[86:89]
	v_mfma_f32_16x16x32_bf16 v[132:135], v[140:143], v[172:175], v[132:135]
	v_mfma_f32_16x16x32_bf16 v[128:131], v[148:151], v[172:175], v[128:131]
	v_mfma_f32_16x16x32_bf16 v[124:127], v[140:143], v[180:183], v[124:127]
	v_mfma_f32_16x16x32_bf16 v[120:123], v[148:151], v[180:183], v[120:123]
	v_mfma_f32_16x16x32_bf16 v[108:111], v[140:143], v[188:191], v[108:111]
	v_mfma_f32_16x16x32_bf16 v[104:107], v[148:151], v[188:191], v[104:107]
	v_mfma_f32_16x16x32_bf16 v[92:95], v[140:143], v[196:199], v[90:93]
	v_mfma_f32_16x16x32_bf16 v[88:91], v[148:151], v[196:199], v[86:89]
	s_setprio 0
	s_setprio 1
	v_mfma_f32_16x16x32_bf16 v[116:119], v[152:155], v[168:171], v[116:119]
	v_mfma_f32_16x16x32_bf16 v[112:115], v[160:163], v[168:171], v[112:115]
	v_mfma_f32_16x16x32_bf16 v[100:103], v[152:155], v[176:179], v[100:103]
	v_mfma_f32_16x16x32_bf16 v[96:99], v[160:163], v[176:179], v[96:99]
	v_mfma_f32_16x16x32_bf16 v[76:79], v[152:155], v[184:187], v[76:79]
	v_mfma_f32_16x16x32_bf16 v[72:75], v[160:163], v[184:187], v[72:75]
	v_mfma_f32_16x16x32_bf16 v[68:71], v[152:155], v[192:195], v[68:71]
	v_mfma_f32_16x16x32_bf16 v[60:63], v[160:163], v[192:195], v[60:63]
	v_mfma_f32_16x16x32_bf16 v[116:119], v[156:159], v[172:175], v[116:119]
	v_mfma_f32_16x16x32_bf16 v[112:115], v[164:167], v[172:175], v[112:115]
	v_mfma_f32_16x16x32_bf16 v[100:103], v[156:159], v[180:183], v[100:103]
	v_mfma_f32_16x16x32_bf16 v[96:99], v[164:167], v[180:183], v[96:99]
	v_mfma_f32_16x16x32_bf16 v[76:79], v[156:159], v[188:191], v[76:79]
	v_mfma_f32_16x16x32_bf16 v[72:75], v[164:167], v[188:191], v[72:75]
	v_mfma_f32_16x16x32_bf16 v[68:71], v[156:159], v[196:199], v[68:71]
	v_mfma_f32_16x16x32_bf16 v[60:63], v[164:167], v[196:199], v[60:63]
	s_setprio 0
	s_barrier
; #define PG8_STAGE(bufoff, gbase, voff) do { _Pragma("unroll") for (int _i = 0; _i < 2; ++_i) { unsigned _vo = (voff)[_i]; asm volatile("" : "+v"(_vo));   \
;         __builtin_amdgcn_global_load_lds((const unsigned*)((const char*)(gbase) + _vo), (LAS unsigned*)(lds + (bufoff) + ldsw + _i * 8192), 16, 0, 0); } } while (0)
; #define PG8_LDA(dst, b, h) do { _Pragma("unroll") for (int m = 0; m < 4; ++m) _Pragma("unroll") for (int k = 0; k < 2; ++k) dst[m][k] = *(const LAS bf16x8*)(lds + PG8_SA(b, h) + aoff + m * 2048 + k * 1024); } while (0)
; #define PG8_MMA(ai, bj, At, Bt) do { __builtin_amdgcn_s_setprio(1); _Pragma("unroll") for (int m = 0; m < 4; ++m) _Pragma("unroll") for (int n = 0; n < 2; ++n) _Pragma("unroll") for (int k = 0; k < 2; ++k) \
;         acc[ai][bj][m][n] = __builtin_amdgcn_mfma_f32_16x16x32_bf16(Bt[n][k], At[m][k], acc[ai][bj][m][n], 0, 0, 0); __builtin_amdgcn_s_setprio(0); } while (0)
; #define PG8_WAIT_V(n) asm volatile("s_waitcnt vmcnt(" #n ")" ::: "memory")
; #define PG8_WAIT_L(n) asm volatile("s_waitcnt lgkmcnt(" #n ")" ::: "memory")
; #define PG8_BAR __builtin_amdgcn_s_barrier()
; #define PG8_SCHED __builtin_amdgcn_sched_barrier(0)
; __device__ __forceinline__ void gemm_phase(LAS unsigned char* lds, const Call& C, const int tid, const Args& args) {
;     ...
;             PG8_LDA(At, 1, 1); PG8_STAGE(PG8_SB(1, 0), b3, voffB); PG8_STAGE(PG8_SB(1, 1), b3 + hstepB, voffB); PG8_STAGE(PG8_SA(1, 0), a3, voffA);
;             PG8_WAIT_V(8); PG8_WAIT_L(0); PG8_BAR; PG8_MMA(1, 0, At, B0); PG8_MMA(1, 1, At, B1); PG8_BAR; PG8_SCHED;
;         }
;         if (wr == 0) PG8_BAR;
	v_mov_b32_e32 v80, v242
	ds_read_b128 v[168:171], v246 offset:49152
	ds_read_b128 v[172:175], v246 offset:50176
	ds_read_b128 v[176:179], v246 offset:51200
	ds_read_b128 v[180:183], v246 offset:52224
	ds_read_b128 v[184:187], v246 offset:53248
	ds_read_b128 v[188:191], v246 offset:54272
	ds_read_b128 v[192:195], v246 offset:55296
	ds_read_b128 v[196:199], v246 offset:56320
	s_add_i32 s24, s24, s23
	v_lshl_add_u64 v[82:83], s[40:41], 0, v[80:81]
	v_lshl_add_u64 v[82:83], v[82:83], 0, s[18:19]
	s_mov_b32 m0, s24
	v_mov_b32_e32 v80, v244
	global_load_lds_dwordx4 v[82:83], off
	s_add_i32 m0, s24, 0x2000
	v_lshl_add_u64 v[82:83], s[40:41], 0, v[80:81]
	v_lshl_add_u64 v[82:83], v[82:83], 0, s[18:19]
	v_mov_b32_e32 v80, v242
	global_load_lds_dwordx4 v[82:83], off
	s_add_i32 s24, s42, s23
	v_lshl_add_u64 v[82:83], s[0:1], 0, v[80:81]
	v_lshl_add_u64 v[82:83], v[82:83], 0, s[18:19]
	s_mov_b32 m0, s24
	v_mov_b32_e32 v80, v244
	global_load_lds_dwordx4 v[82:83], off
	s_add_i32 m0, s24, 0x2000
	v_lshl_add_u64 v[82:83], s[0:1], 0, v[80:81]
	v_lshl_add_u64 v[82:83], v[82:83], 0, s[18:19]
	v_mov_b32_e32 v80, v205
	global_load_lds_dwordx4 v[82:83], off
	s_mov_b32 m0, s14
	v_lshl_add_u64 v[82:83], s[38:39], 0, v[80:81]
	v_lshl_add_u64 v[82:83], v[82:83], 0, s[18:19]
	v_mov_b32_e32 v80, v243
	global_load_lds_dwordx4 v[82:83], off
	s_mov_b32 m0, s52
	v_lshl_add_u64 v[82:83], s[38:39], 0, v[80:81]
	v_lshl_add_u64 v[82:83], v[82:83], 0, s[18:19]
	global_load_lds_dwordx4 v[82:83], off
	s_waitcnt vmcnt(8)
	s_waitcnt lgkmcnt(0)
	s_barrier
	s_setprio 1
	s_waitcnt lgkmcnt(0)
	v_mfma_f32_16x16x32_bf16 v[64:67], v[136:139], v[168:171], v[64:67]
	v_mfma_f32_16x16x32_bf16 v[56:59], v[144:147], v[168:171], v[56:59]
	v_mfma_f32_16x16x32_bf16 v[52:55], v[136:139], v[176:179], v[52:55]
	v_mfma_f32_16x16x32_bf16 v[48:51], v[144:147], v[176:179], v[48:51]
	v_mfma_f32_16x16x32_bf16 v[36:39], v[136:139], v[184:187], v[36:39]
	v_mfma_f32_16x16x32_bf16 v[32:35], v[144:147], v[184:187], v[32:35]
	v_mfma_f32_16x16x32_bf16 v[20:23], v[136:139], v[192:195], v[20:23]
	v_mfma_f32_16x16x32_bf16 v[16:19], v[144:147], v[192:195], v[16:19]
	v_mfma_f32_16x16x32_bf16 v[64:67], v[140:143], v[172:175], v[64:67]
	v_mfma_f32_16x16x32_bf16 v[56:59], v[148:151], v[172:175], v[56:59]
	v_mfma_f32_16x16x32_bf16 v[52:55], v[140:143], v[180:183], v[52:55]
	v_mfma_f32_16x16x32_bf16 v[48:51], v[148:151], v[180:183], v[48:51]
	v_mfma_f32_16x16x32_bf16 v[36:39], v[140:143], v[188:191], v[36:39]
	v_mfma_f32_16x16x32_bf16 v[32:35], v[148:151], v[188:191], v[32:35]
	v_mfma_f32_16x16x32_bf16 v[20:23], v[140:143], v[196:199], v[20:23]
	v_mfma_f32_16x16x32_bf16 v[16:19], v[148:151], v[196:199], v[16:19]
	s_setprio 0
	s_setprio 1
	v_mfma_f32_16x16x32_bf16 v[44:47], v[152:155], v[168:171], v[44:47]
	v_mfma_f32_16x16x32_bf16 v[40:43], v[160:163], v[168:171], v[40:43]
	v_mfma_f32_16x16x32_bf16 v[28:31], v[152:155], v[176:179], v[28:31]
	v_mfma_f32_16x16x32_bf16 v[24:27], v[160:163], v[176:179], v[24:27]
	v_mfma_f32_16x16x32_bf16 v[12:15], v[152:155], v[184:187], v[12:15]
	v_mfma_f32_16x16x32_bf16 v[8:11], v[160:163], v[184:187], v[8:11]
	v_mfma_f32_16x16x32_bf16 v[4:7], v[152:155], v[192:195], v[4:7]
	v_mfma_f32_16x16x32_bf16 v[0:3], v[160:163], v[192:195], v[0:3]
	v_mfma_f32_16x16x32_bf16 v[44:47], v[156:159], v[172:175], v[44:47]
	v_mfma_f32_16x16x32_bf16 v[40:43], v[164:167], v[172:175], v[40:43]
	v_mfma_f32_16x16x32_bf16 v[28:31], v[156:159], v[180:183], v[28:31]
	v_mfma_f32_16x16x32_bf16 v[24:27], v[164:167], v[180:183], v[24:27]
	v_mfma_f32_16x16x32_bf16 v[12:15], v[156:159], v[188:191], v[12:15]
	v_mfma_f32_16x16x32_bf16 v[8:11], v[164:167], v[188:191], v[8:11]
	v_mfma_f32_16x16x32_bf16 v[4:7], v[156:159], v[196:199], v[4:7]
	v_mfma_f32_16x16x32_bf16 v[0:3], v[164:167], v[196:199], v[0:3]
	s_setprio 0
	s_barrier
	s_add_u32 s16, s16, 0x100
	s_addc_u32 s17, s17, 0
	s_cmp_ge_u32 s25, s12
	s_mov_b64 s[0:1], s[8:9]
	s_mov_b32 s24, s25
	s_cbranch_scc0 .LBB0_282
	s_and_b64 vcc, exec, s[80:81]
	s_cbranch_vccz .LBB0_285
